# P0 rmsnorm row loop: two rows in flight per wave (double-buffered row loads, counted vmcnt) on top of v_comb
# baseline (speedup 1.0000x reference)
;     ...
;     const float* g1 = a.in[1];
;     f32x4 gv[4];
; #pragma unroll
;     for (int j = 0; j < 4; ++j) gv[j] = ((const f32x4*)g1)[lane + 64 * j];
;     for (int m = gw; m < M; m += NGW) {
;         const f32x4* xr = (const f32x4*)(a.in[0] + (size_t)m * D) + lane;
;         f32x4 v[4]; float s = 0.f;
; #pragma unroll
;         for (int j = 0; j < 4; ++j) { v[j] = xr[64 * j]; s += (v[j].x * v[j].x + v[j].y * v[j].y) + (v[j].z * v[j].z + v[j].w * v[j].w); }
;         const float rstd = __builtin_amdgcn_rsqf(wave_sum(s) * (1.f / D) + EPS);
.LBB0_28:
	s_cmpk_gt_i32 s2, 0x3fff
	s_cbranch_scc1 .LBB0_31
	s_waitcnt vmcnt(17)
	v_lshlrev_b32_e32 v18, 4, v180
	s_waitcnt lgkmcnt(0)
	global_load_dwordx4 v[0:3], v18, s[54:55]
	global_load_dwordx4 v[4:7], v18, s[54:55] offset:1024
	global_load_dwordx4 v[8:11], v18, s[54:55] offset:2048
	global_load_dwordx4 v[12:15], v18, s[54:55] offset:3072
	v_mbcnt_lo_u32_b32 v16, -1, 0
	v_mbcnt_hi_u32_b32 v16, -1, v16
	v_and_b32_e32 v17, 64, v16
	v_add_u32_e32 v17, 64, v17
	s_waitcnt vmcnt(19)
	v_xor_b32_e32 v20, 1, v16
	v_cmp_lt_i32_e32 vcc, v20, v17
	s_waitcnt vmcnt(18)
	v_xor_b32_e32 v21, 2, v16
	s_waitcnt vmcnt(17)
	v_xor_b32_e32 v22, 4, v16
	v_cndmask_b32_e32 v20, v16, v20, vcc
	v_cmp_lt_i32_e32 vcc, v21, v17
	s_waitcnt vmcnt(16)
	v_xor_b32_e32 v23, 8, v16
	s_waitcnt vmcnt(15)
	v_xor_b32_e32 v24, 16, v16
	v_cndmask_b32_e32 v21, v16, v21, vcc
	v_cmp_lt_i32_e32 vcc, v22, v17
	s_waitcnt vmcnt(14)
	v_xor_b32_e32 v25, 32, v16
	s_ashr_i32 s3, s2, 31
	v_cndmask_b32_e32 v22, v16, v22, vcc
	v_cmp_lt_i32_e32 vcc, v23, v17
	s_lshl_b64 s[6:7], s[2:3], 11
	v_mov_b32_e32 v19, 0
	v_cndmask_b32_e32 v23, v16, v23, vcc
	v_cmp_lt_i32_e32 vcc, v24, v17
	s_add_u32 s6, s72, s6
	s_addc_u32 s7, s73, s7
	v_cndmask_b32_e32 v24, v16, v24, vcc
	v_cmp_lt_i32_e32 vcc, v25, v17
	v_mov_b32_e32 v17, v19
	s_ashr_i32 s5, s4, 31
	v_cndmask_b32_e32 v16, v16, v25, vcc
	v_lshlrev_b32_e32 v25, 2, v16
	v_lshlrev_b32_e32 v16, 3, v180
	v_lshl_add_u64 v[16:17], s[6:7], 0, v[16:17]
	s_mov_b64 s[6:7], 0x2b00000
	v_lshl_add_u64 v[16:17], v[16:17], 0, s[6:7]
	s_lshl_b64 s[6:7], s[4:5], 11
	s_lshl_b64 s[8:9], s[2:3], 12
	s_add_u32 s8, s52, s8
	s_addc_u32 s9, s53, s9
	v_lshl_add_u64 v[18:19], s[8:9], 0, v[18:19]
	s_mov_b64 s[8:9], 0xc00
	v_lshlrev_b32_e32 v20, 2, v20
	v_lshlrev_b32_e32 v21, 2, v21
	v_lshlrev_b32_e32 v22, 2, v22
	v_lshlrev_b32_e32 v23, 2, v23
	v_lshlrev_b32_e32 v24, 2, v24
	v_lshl_add_u64 v[18:19], v[18:19], 0, s[8:9]
	s_lshl_b64 s[8:9], s[4:5], 12
	s_waitcnt vmcnt(13)
	v_mov_b32_e32 v26, 0x358637bd
	s_movk_i32 s3, 0x7fff
	s_mov_b32 s5, 0xffff0000
	global_load_dwordx4 v[28:31], v[18:19], off offset:-3072
	global_load_dwordx4 v[32:35], v[18:19], off offset:-2048
	global_load_dwordx4 v[36:39], v[18:19], off
	global_load_dwordx4 v[40:43], v[18:19], off offset:-1024
	s_add_i32 s2, s2, s4
	v_lshl_add_u64 v[18:19], v[18:19], 0, s[8:9]
	s_mov_b32 vcc_lo, 0
	s_mov_b32 vcc_hi, 0
	s_cmpk_lt_i32 s2, 0x4000
	s_cbranch_scc0 .Lmy_p0_A
	global_load_dwordx4 v[130:133], v[18:19], off offset:-3072
	global_load_dwordx4 v[134:137], v[18:19], off offset:-2048
	global_load_dwordx4 v[138:141], v[18:19], off
	global_load_dwordx4 v[142:145], v[18:19], off offset:-1024
	s_add_i32 s2, s2, s4
	v_lshl_add_u64 v[18:19], v[18:19], 0, s[8:9]
	s_mov_b32 vcc_lo, 4
	s_mov_b32 vcc_hi, 1
.Lmy_p0_A:
	s_cmp_eq_u32 vcc_lo, 8
	s_cbranch_scc1 .Lmy_p0_A_w8
	s_cmp_eq_u32 vcc_lo, 4
	s_cbranch_scc1 .Lmy_p0_A_w4
	s_waitcnt vmcnt(0)
	s_branch .Lmy_p0_A_go
.Lmy_p0_A_w4:
	s_waitcnt vmcnt(4)
	s_branch .Lmy_p0_A_go
.Lmy_p0_A_w8:
	s_waitcnt vmcnt(8)
; __device__ __forceinline__ unsigned pk2(float lo, float hi) { return f2bf(lo) | (f2bf(hi) << 16); }
;     ...
;     for (int m = gw; m < M; m += NGW) {
;         const f32x4* xr = (const f32x4*)(a.in[0] + (size_t)m * D) + lane;
;         f32x4 v[4]; float s = 0.f;
; #pragma unroll
;         for (int j = 0; j < 4; ++j) { v[j] = xr[64 * j]; s += (v[j].x * v[j].x + v[j].y * v[j].y) + (v[j].z * v[j].z + v[j].w * v[j].w); }
;         const float rstd = __builtin_amdgcn_rsqf(wave_sum(s) * (1.f / D) + EPS);
;         unsigned long long* o8 = (unsigned long long*)((bf16*)(ws + WS_H) + (size_t)m * D) + lane;
; #pragma unroll
;         for (int j = 0; j < 4; ++j) { const f32x4 y = v[j] * rstd * gv[j]; o8[64 * j] = (unsigned long long)pk2(y.x, y.y) | ((unsigned long long)pk2(y.z, y.w) << 32); }
;     }
.Lmy_p0_A_go:
	v_pk_mul_f32 v[44:45], v[30:31], v[30:31]
	v_pk_mul_f32 v[46:47], v[28:29], v[28:29]
	v_pk_mul_f32 v[48:49], v[34:35], v[34:35]
	v_pk_mul_f32 v[50:51], v[32:33], v[32:33]
	v_pk_mov_b32 v[56:57], v[46:47], v[44:45] op_sel:[1,0]
	v_mov_b32_e32 v47, v45
	v_pk_mov_b32 v[44:45], v[50:51], v[48:49] op_sel:[1,0]
	v_mov_b32_e32 v51, v49
	v_mul_f32_e32 v55, v37, v37
	v_mul_f32_e32 v52, v41, v41
	v_mul_f32_e32 v54, v43, v43
	v_pk_add_f32 v[46:47], v[56:57], v[46:47]
	v_pk_add_f32 v[44:45], v[44:45], v[50:51]
	v_mul_f32_e32 v27, v36, v36
	v_mul_f32_e32 v58, v38, v38
	v_mul_f32_e32 v59, v39, v39
	v_pk_fma_f32 v[48:49], v[40:41], v[40:41], v[52:53] op_sel_hi:[1,1,0]
	v_pk_fma_f32 v[52:53], v[42:43], v[42:43], v[54:55] op_sel_hi:[1,1,0]
	v_pk_add_f32 v[46:47], v[46:47], v[46:47] op_sel:[0,1] op_sel_hi:[1,0]
	v_pk_add_f32 v[44:45], v[44:45], v[44:45] op_sel:[0,1] op_sel_hi:[1,0]
	v_mov_b32_e32 v49, v58
	v_mov_b32_e32 v53, v59
	v_mov_b32_e32 v47, v27
	v_mov_b32_e32 v45, v55
	v_pk_add_f32 v[48:49], v[48:49], v[52:53]
	v_pk_add_f32 v[44:45], v[46:47], v[44:45]
	s_nop 0
	v_pk_add_f32 v[44:45], v[44:45], v[48:49]
	s_nop 0
	v_add_f32_e32 v27, v44, v45
	ds_bpermute_b32 v44, v20, v27
	s_waitcnt lgkmcnt(0)
	v_add_f32_e32 v27, v27, v44
	ds_bpermute_b32 v44, v21, v27
	s_waitcnt lgkmcnt(0)
	v_add_f32_e32 v27, v27, v44
	ds_bpermute_b32 v44, v22, v27
	s_waitcnt lgkmcnt(0)
	v_add_f32_e32 v27, v27, v44
	ds_bpermute_b32 v44, v23, v27
	s_waitcnt lgkmcnt(0)
	v_add_f32_e32 v27, v27, v44
	ds_bpermute_b32 v44, v24, v27
	s_waitcnt lgkmcnt(0)
	v_add_f32_e32 v27, v27, v44
	ds_bpermute_b32 v44, v25, v27
	s_waitcnt lgkmcnt(0)
	v_add_f32_e32 v27, v27, v44
	v_fmamk_f32 v27, v27, 0x3a800000, v26
	v_rsq_f32_e32 v44, v27
	s_nop 0
	v_pk_mul_f32 v[28:29], v[28:29], v[44:45] op_sel_hi:[1,0]
	v_pk_mul_f32 v[30:31], v[30:31], v[44:45] op_sel_hi:[1,0]
	v_pk_mul_f32 v[32:33], v[32:33], v[44:45] op_sel_hi:[1,0]
	v_pk_mul_f32 v[34:35], v[34:35], v[44:45] op_sel_hi:[1,0]
	v_pk_mul_f32 v[40:41], v[40:41], v[44:45] op_sel_hi:[1,0]
	v_pk_mul_f32 v[42:43], v[42:43], v[44:45] op_sel_hi:[1,0]
	v_pk_mul_f32 v[36:37], v[36:37], v[44:45] op_sel_hi:[1,0]
	v_pk_mul_f32 v[38:39], v[38:39], v[44:45] op_sel_hi:[1,0]
	v_pk_mul_f32 v[30:31], v[2:3], v[30:31]
	v_pk_mul_f32 v[28:29], v[0:1], v[28:29]
	v_pk_mul_f32 v[34:35], v[6:7], v[34:35]
	v_pk_mul_f32 v[32:33], v[4:5], v[32:33]
	v_pk_mul_f32 v[42:43], v[10:11], v[42:43]
	v_pk_mul_f32 v[40:41], v[8:9], v[40:41]
	v_pk_mul_f32 v[38:39], v[14:15], v[38:39]
	v_pk_mul_f32 v[36:37], v[12:13], v[36:37]
	v_bfe_u32 v27, v28, 16, 1
	v_bfe_u32 v44, v29, 16, 1
	v_bfe_u32 v45, v30, 16, 1
	v_bfe_u32 v46, v31, 16, 1
	v_bfe_u32 v47, v32, 16, 1
	v_bfe_u32 v48, v33, 16, 1
	v_bfe_u32 v49, v34, 16, 1
	v_bfe_u32 v50, v35, 16, 1
	v_bfe_u32 v51, v40, 16, 1
	v_bfe_u32 v52, v41, 16, 1
	v_bfe_u32 v53, v42, 16, 1
	v_bfe_u32 v55, v36, 16, 1
	v_bfe_u32 v57, v38, 16, 1
	v_add3_u32 v27, v28, v27, s3
	v_add3_u32 v28, v29, v44, s3
	v_add3_u32 v29, v30, v45, s3
	v_bfe_u32 v54, v43, 16, 1
	v_bfe_u32 v56, v37, 16, 1
	v_bfe_u32 v58, v39, 16, 1
	v_add3_u32 v30, v31, v46, s3
	v_add3_u32 v31, v32, v47, s3
	v_add3_u32 v32, v33, v48, s3
	v_add3_u32 v33, v34, v49, s3
	v_add3_u32 v34, v35, v50, s3
	v_add3_u32 v35, v40, v51, s3
	v_add3_u32 v40, v41, v52, s3
	v_add3_u32 v41, v42, v53, s3
	v_add3_u32 v36, v36, v55, s3
	v_add3_u32 v38, v38, v57, s3
	v_lshrrev_b32_e32 v27, 16, v27
	v_lshrrev_b32_e32 v29, 16, v29
	v_add3_u32 v42, v43, v54, s3
	v_add3_u32 v37, v37, v56, s3
	v_add3_u32 v39, v39, v58, s3
	v_lshrrev_b32_e32 v31, 16, v31
	v_lshrrev_b32_e32 v33, 16, v33
	v_lshrrev_b32_e32 v35, 16, v35
	v_lshrrev_b32_e32 v41, 16, v41
	v_lshrrev_b32_e32 v36, 16, v36
	v_lshrrev_b32_e32 v38, 16, v38
	v_and_or_b32 v28, v28, s5, v27
	v_and_or_b32 v29, v30, s5, v29
	v_and_or_b32 v30, v32, s5, v31
	v_and_or_b32 v31, v34, s5, v33
	v_and_or_b32 v32, v40, s5, v35
	v_and_or_b32 v33, v42, s5, v41
	v_and_or_b32 v34, v37, s5, v36
	v_and_or_b32 v35, v39, s5, v38
	global_store_dwordx2 v[16:17], v[28:29], off
	global_store_dwordx2 v[16:17], v[30:31], off offset:512
	global_store_dwordx2 v[16:17], v[32:33], off offset:1024
	global_store_dwordx2 v[16:17], v[34:35], off offset:1536
	v_lshl_add_u64 v[16:17], v[16:17], 0, s[6:7]
	s_cmp_eq_u32 vcc_hi, 0
	s_cbranch_scc1 .LBB0_31
	s_mov_b32 vcc_lo, 4
	s_mov_b32 vcc_hi, 0
	s_cmpk_lt_i32 s2, 0x4000
	s_cbranch_scc0 .Lmy_p0_B
	global_load_dwordx4 v[28:31], v[18:19], off offset:-3072
	global_load_dwordx4 v[32:35], v[18:19], off offset:-2048
	global_load_dwordx4 v[36:39], v[18:19], off
	global_load_dwordx4 v[40:43], v[18:19], off offset:-1024
	s_add_i32 s2, s2, s4
	v_lshl_add_u64 v[18:19], v[18:19], 0, s[8:9]
	s_mov_b32 vcc_lo, 8
	s_mov_b32 vcc_hi, 1

; __device__ __forceinline__ unsigned pk2(float lo, float hi) { return f2bf(lo) | (f2bf(hi) << 16); }
;     ...
;     for (int m = gw; m < M; m += NGW) {
;         const f32x4* xr = (const f32x4*)(a.in[0] + (size_t)m * D) + lane;
;         f32x4 v[4]; float s = 0.f;
; #pragma unroll
;         for (int j = 0; j < 4; ++j) { v[j] = xr[64 * j]; s += (v[j].x * v[j].x + v[j].y * v[j].y) + (v[j].z * v[j].z + v[j].w * v[j].w); }
;         const float rstd = __builtin_amdgcn_rsqf(wave_sum(s) * (1.f / D) + EPS);
;         unsigned long long* o8 = (unsigned long long*)((bf16*)(ws + WS_H) + (size_t)m * D) + lane;
; #pragma unroll
;         for (int j = 0; j < 4; ++j) { const f32x4 y = v[j] * rstd * gv[j]; o8[64 * j] = (unsigned long long)pk2(y.x, y.y) | ((unsigned long long)pk2(y.z, y.w) << 32); }
;     }
.Lmy_p0_B_go:
	v_pk_mul_f32 v[44:45], v[132:133], v[132:133]
	v_pk_mul_f32 v[46:47], v[130:131], v[130:131]
	v_pk_mul_f32 v[48:49], v[136:137], v[136:137]
	v_pk_mul_f32 v[50:51], v[134:135], v[134:135]
	v_pk_mov_b32 v[56:57], v[46:47], v[44:45] op_sel:[1,0]
	v_mov_b32_e32 v47, v45
	v_pk_mov_b32 v[44:45], v[50:51], v[48:49] op_sel:[1,0]
	v_mov_b32_e32 v51, v49
	v_mul_f32_e32 v55, v139, v139
	v_mul_f32_e32 v52, v143, v143
	v_mul_f32_e32 v54, v145, v145
	v_pk_add_f32 v[46:47], v[56:57], v[46:47]
	v_pk_add_f32 v[44:45], v[44:45], v[50:51]
	v_mul_f32_e32 v27, v138, v138
	v_mul_f32_e32 v58, v140, v140
	v_mul_f32_e32 v59, v141, v141
	v_pk_fma_f32 v[48:49], v[142:143], v[142:143], v[52:53] op_sel_hi:[1,1,0]
	v_pk_fma_f32 v[52:53], v[144:145], v[144:145], v[54:55] op_sel_hi:[1,1,0]
	v_pk_add_f32 v[46:47], v[46:47], v[46:47] op_sel:[0,1] op_sel_hi:[1,0]
	v_pk_add_f32 v[44:45], v[44:45], v[44:45] op_sel:[0,1] op_sel_hi:[1,0]
	v_mov_b32_e32 v49, v58
	v_mov_b32_e32 v53, v59
	v_mov_b32_e32 v47, v27
	v_mov_b32_e32 v45, v55
	v_pk_add_f32 v[48:49], v[48:49], v[52:53]
	v_pk_add_f32 v[44:45], v[46:47], v[44:45]
	s_nop 0
	v_pk_add_f32 v[44:45], v[44:45], v[48:49]
	s_nop 0
	v_add_f32_e32 v27, v44, v45
	ds_bpermute_b32 v44, v20, v27
	s_waitcnt lgkmcnt(0)
	v_add_f32_e32 v27, v27, v44
	ds_bpermute_b32 v44, v21, v27
	s_waitcnt lgkmcnt(0)
	v_add_f32_e32 v27, v27, v44
	ds_bpermute_b32 v44, v22, v27
	s_waitcnt lgkmcnt(0)
	v_add_f32_e32 v27, v27, v44
	ds_bpermute_b32 v44, v23, v27
	s_waitcnt lgkmcnt(0)
	v_add_f32_e32 v27, v27, v44
	ds_bpermute_b32 v44, v24, v27
	s_waitcnt lgkmcnt(0)
	v_add_f32_e32 v27, v27, v44
	ds_bpermute_b32 v44, v25, v27
	s_waitcnt lgkmcnt(0)
	v_add_f32_e32 v27, v27, v44
	v_fmamk_f32 v27, v27, 0x3a800000, v26
	v_rsq_f32_e32 v44, v27
	s_nop 0
	v_pk_mul_f32 v[130:131], v[130:131], v[44:45] op_sel_hi:[1,0]
	v_pk_mul_f32 v[132:133], v[132:133], v[44:45] op_sel_hi:[1,0]
	v_pk_mul_f32 v[134:135], v[134:135], v[44:45] op_sel_hi:[1,0]
	v_pk_mul_f32 v[136:137], v[136:137], v[44:45] op_sel_hi:[1,0]
	v_pk_mul_f32 v[142:143], v[142:143], v[44:45] op_sel_hi:[1,0]
	v_pk_mul_f32 v[144:145], v[144:145], v[44:45] op_sel_hi:[1,0]
	v_pk_mul_f32 v[138:139], v[138:139], v[44:45] op_sel_hi:[1,0]
	v_pk_mul_f32 v[140:141], v[140:141], v[44:45] op_sel_hi:[1,0]
	v_pk_mul_f32 v[132:133], v[2:3], v[132:133]
	v_pk_mul_f32 v[130:131], v[0:1], v[130:131]
	v_pk_mul_f32 v[136:137], v[6:7], v[136:137]
	v_pk_mul_f32 v[134:135], v[4:5], v[134:135]
	v_pk_mul_f32 v[144:145], v[10:11], v[144:145]
	v_pk_mul_f32 v[142:143], v[8:9], v[142:143]
	v_pk_mul_f32 v[140:141], v[14:15], v[140:141]
	v_pk_mul_f32 v[138:139], v[12:13], v[138:139]
	v_bfe_u32 v27, v130, 16, 1
	v_bfe_u32 v44, v131, 16, 1
	v_bfe_u32 v45, v132, 16, 1
	v_bfe_u32 v46, v133, 16, 1
	v_bfe_u32 v47, v134, 16, 1
	v_bfe_u32 v48, v135, 16, 1
	v_bfe_u32 v49, v136, 16, 1
	v_bfe_u32 v50, v137, 16, 1
	v_bfe_u32 v51, v142, 16, 1
	v_bfe_u32 v52, v143, 16, 1
	v_bfe_u32 v53, v144, 16, 1
	v_bfe_u32 v55, v138, 16, 1
	v_bfe_u32 v57, v140, 16, 1
	v_add3_u32 v27, v130, v27, s3
	v_add3_u32 v130, v131, v44, s3
	v_add3_u32 v131, v132, v45, s3
	v_bfe_u32 v54, v145, 16, 1
	v_bfe_u32 v56, v139, 16, 1
	v_bfe_u32 v58, v141, 16, 1
	v_add3_u32 v132, v133, v46, s3
	v_add3_u32 v133, v134, v47, s3
	v_add3_u32 v134, v135, v48, s3
	v_add3_u32 v135, v136, v49, s3
	v_add3_u32 v136, v137, v50, s3
	v_add3_u32 v137, v142, v51, s3
	v_add3_u32 v142, v143, v52, s3
	v_add3_u32 v143, v144, v53, s3
	v_add3_u32 v138, v138, v55, s3
	v_add3_u32 v140, v140, v57, s3
	v_lshrrev_b32_e32 v27, 16, v27
	v_lshrrev_b32_e32 v131, 16, v131
	v_add3_u32 v144, v145, v54, s3
	v_add3_u32 v139, v139, v56, s3
	v_add3_u32 v141, v141, v58, s3
	v_lshrrev_b32_e32 v133, 16, v133
	v_lshrrev_b32_e32 v135, 16, v135
	v_lshrrev_b32_e32 v137, 16, v137
	v_lshrrev_b32_e32 v143, 16, v143
	v_lshrrev_b32_e32 v138, 16, v138
	v_lshrrev_b32_e32 v140, 16, v140
	v_and_or_b32 v130, v130, s5, v27
	v_and_or_b32 v131, v132, s5, v131
	v_and_or_b32 v132, v134, s5, v133
	v_and_or_b32 v133, v136, s5, v135
	v_and_or_b32 v134, v142, s5, v137
	v_and_or_b32 v135, v144, s5, v143
	v_and_or_b32 v136, v139, s5, v138
	v_and_or_b32 v137, v141, s5, v140
	global_store_dwordx2 v[16:17], v[130:131], off
	global_store_dwordx2 v[16:17], v[132:133], off offset:512
	global_store_dwordx2 v[16:17], v[134:135], off offset:1024
	global_store_dwordx2 v[16:17], v[136:137], off offset:1536
	v_lshl_add_u64 v[16:17], v[16:17], 0, s[6:7]
	s_cmp_eq_u32 vcc_hi, 0
	s_cbranch_scc1 .LBB0_31
	s_mov_b32 vcc_lo, 4
	s_mov_b32 vcc_hi, 0
	s_cmpk_lt_i32 s2, 0x4000
	s_cbranch_scc0 .Lmy_p0_A
	global_load_dwordx4 v[130:133], v[18:19], off offset:-3072
	global_load_dwordx4 v[134:137], v[18:19], off offset:-2048
	global_load_dwordx4 v[138:141], v[18:19], off
	global_load_dwordx4 v[142:145], v[18:19], off offset:-1024
	s_add_i32 s2, s2, s4
	v_lshl_add_u64 v[18:19], v[18:19], 0, s[8:9]
	s_mov_b32 vcc_lo, 8
	s_mov_b32 vcc_hi, 1
	s_branch .Lmy_p0_A
